# RG-LRU mode-0 tile loop: conv-input LDS reads batched too
# baseline (speedup 1.0000x reference)
; DI bf16_t f2bf(float a) { return (bf16_t)(pk2(a, 0.f) & 0xffffu); }
; DI float bf2f(unsigned b) { return __uint_as_float(b << 16); }
; DI void phase_lru(const Params& p, int layer, int b0, int nb, int mode, bool skipctx, char* smem) {
;     ...
;     const int s0 = j * 64, slo = j < 4 ? 0 : LC, shi = j < 4 ? LC : S;
;     { const int row = tid >> 3, kc = tid & 7, s = s0 - 2 + row;
;       pre0 = make_uint4(0, 0, 0, 0);
;       if (s >= slo && s < shi) pre0 = *(const uint4*)(Z + ((size_t)b * S + s) * ZS + Z_LRUX + nblk * 64 + kc * 8); }
;     { const int c = tid + 512, row = c >> 3, kc = c & 7, s = s0 - 2 + row;
;       pre1 = make_uint4(0, 0, 0, 0);
;       if (c < 67 * 8 && s >= slo && s < shi) pre1 = *(const uint4*)(Z + ((size_t)b * S + s) * ZS + Z_LRUX + nblk * 64 + kc * 8); }
;     ...
;     __syncthreads();
; #pragma unroll
;     for (int i = 0; i < 8; ++i) {
;       const int tok = (tid >> 6) + 8 * i;
;       const float u = bb + w0 * bf2f(xs[tok * 64 + ch]) + w1 * bf2f(xs[(tok + 1) * 64 + ch]) + w2 * bf2f(xs[(tok + 2) * 64 + ch]) + w3 * bf2f(xs[(tok + 3) * 64 + ch]);
;       uF[tok * 64 + ch] = u; uA[tok * 72 + ch] = f2bf(u);
;     }
.LBB0_559:
	s_mul_i32 s0, s13, 0x2200
	v_mov_b32_e32 v80, v192
	s_add_i32 s0, s0, 0
	s_waitcnt lgkmcnt(0)
	v_and_b32_e32 v81, 63, v80
	v_and_b32_e32 v1, 0x7fffffc0, v80
	v_lshlrev_b32_e32 v0, 1, v81
	v_lshl_add_u32 v2, v80, 1, s0
	v_lshlrev_b32_e32 v1, 1, v1
	s_barrier
	ds_read_u16 v134, v2
	ds_read_u16 v135, v2 offset:128
	ds_read_u16 v136, v2 offset:256
	ds_read_u16 v137, v2 offset:384
	ds_read_u16 v138, v2 offset:1024
	ds_read_u16 v139, v2 offset:1152
	ds_read_u16 v140, v2 offset:1280
	ds_read_u16 v141, v2 offset:1408
	ds_read_u16 v142, v2 offset:2048
	ds_read_u16 v143, v2 offset:2176
	ds_read_u16 v144, v2 offset:2304
	ds_read_u16 v145, v2 offset:2432
	ds_read_u16 v146, v2 offset:3072
	ds_read_u16 v147, v2 offset:3200
	ds_read_u16 v148, v2 offset:3328
	ds_read_u16 v149, v2 offset:3456
	ds_read_u16 v150, v2 offset:4096
	ds_read_u16 v151, v2 offset:4224
	ds_read_u16 v152, v2 offset:4352
	ds_read_u16 v153, v2 offset:4480
	ds_read_u16 v154, v2 offset:5120
	ds_read_u16 v155, v2 offset:5248
	ds_read_u16 v156, v2 offset:5376
	ds_read_u16 v157, v2 offset:5504
	ds_read_u16 v158, v2 offset:6144
	ds_read_u16 v159, v2 offset:6272
	ds_read_u16 v160, v2 offset:6400
	ds_read_u16 v161, v2 offset:6528
	ds_read_u16 v162, v2 offset:7168
	ds_read_u16 v163, v2 offset:7296
	ds_read_u16 v164, v2 offset:7424
	ds_read_u16 v165, v2 offset:7552
	v_ashrrev_i32_e32 v82, 6, v80
	v_lshl_add_u32 v176, v80, 2, 0
	v_mul_lo_u32 v175, v82, s21
	v_add3_u32 v175, 0, v0, v175
	s_waitcnt lgkmcnt(15)
	v_lshlrev_b32_e32 v134, 16, v134
	v_lshlrev_b32_e32 v135, 16, v135
	v_lshlrev_b32_e32 v136, 16, v136
	v_lshlrev_b32_e32 v137, 16, v137
	v_fma_f32 v166, v75, v134, v78
	v_fmac_f32_e32 v166, v76, v135
	v_fmac_f32_e32 v166, v77, v136
	v_fmac_f32_e32 v166, v79, v137
	ds_write_b32 v176, v166 offset:26624
	v_cvt_pk_bf16_f32 v174, v166, v166
	ds_write_b16 v175, v174 offset:17408
	s_waitcnt lgkmcnt(15)
	v_lshlrev_b32_e32 v138, 16, v138
	v_lshlrev_b32_e32 v139, 16, v139
	v_lshlrev_b32_e32 v140, 16, v140
	v_lshlrev_b32_e32 v141, 16, v141
	v_fma_f32 v167, v75, v138, v78
	v_fmac_f32_e32 v167, v76, v139
	v_fmac_f32_e32 v167, v77, v140
	v_fmac_f32_e32 v167, v79, v141
	ds_write_b32 v176, v167 offset:28672
	v_cvt_pk_bf16_f32 v174, v167, v167
	ds_write_b16 v175, v174 offset:18560
	s_waitcnt lgkmcnt(15)
	v_lshlrev_b32_e32 v142, 16, v142
	v_lshlrev_b32_e32 v143, 16, v143
	v_lshlrev_b32_e32 v144, 16, v144
	v_lshlrev_b32_e32 v145, 16, v145
	v_fma_f32 v168, v75, v142, v78
	v_fmac_f32_e32 v168, v76, v143
	v_fmac_f32_e32 v168, v77, v144
	v_fmac_f32_e32 v168, v79, v145
	ds_write_b32 v176, v168 offset:30720
	v_cvt_pk_bf16_f32 v174, v168, v168
	ds_write_b16 v175, v174 offset:19712
	s_waitcnt lgkmcnt(15)
	v_lshlrev_b32_e32 v146, 16, v146
	v_lshlrev_b32_e32 v147, 16, v147
	v_lshlrev_b32_e32 v148, 16, v148
	v_lshlrev_b32_e32 v149, 16, v149
	v_fma_f32 v169, v75, v146, v78
	v_fmac_f32_e32 v169, v76, v147
	v_fmac_f32_e32 v169, v77, v148
	v_fmac_f32_e32 v169, v79, v149
	ds_write_b32 v176, v169 offset:32768
	v_cvt_pk_bf16_f32 v174, v169, v169
	ds_write_b16 v175, v174 offset:20864
	s_waitcnt lgkmcnt(15)
	v_lshlrev_b32_e32 v150, 16, v150
	v_lshlrev_b32_e32 v151, 16, v151
	v_lshlrev_b32_e32 v152, 16, v152
	v_lshlrev_b32_e32 v153, 16, v153
	v_fma_f32 v170, v75, v150, v78
	v_fmac_f32_e32 v170, v76, v151
	v_fmac_f32_e32 v170, v77, v152
	v_fmac_f32_e32 v170, v79, v153
	ds_write_b32 v176, v170 offset:34816
	v_cvt_pk_bf16_f32 v174, v170, v170
	ds_write_b16 v175, v174 offset:22016
	s_waitcnt lgkmcnt(15)
	v_lshlrev_b32_e32 v154, 16, v154
	v_lshlrev_b32_e32 v155, 16, v155
	v_lshlrev_b32_e32 v156, 16, v156
	v_lshlrev_b32_e32 v157, 16, v157
	v_fma_f32 v171, v75, v154, v78
	v_fmac_f32_e32 v171, v76, v155
	v_fmac_f32_e32 v171, v77, v156
	v_fmac_f32_e32 v171, v79, v157
	ds_write_b32 v176, v171 offset:36864
	v_cvt_pk_bf16_f32 v174, v171, v171
	ds_write_b16 v175, v174 offset:23168
	s_waitcnt lgkmcnt(15)
	v_lshlrev_b32_e32 v158, 16, v158
	v_lshlrev_b32_e32 v159, 16, v159
	v_lshlrev_b32_e32 v160, 16, v160
	v_lshlrev_b32_e32 v161, 16, v161
	v_fma_f32 v172, v75, v158, v78
	v_fmac_f32_e32 v172, v76, v159
	v_fmac_f32_e32 v172, v77, v160
	v_fmac_f32_e32 v172, v79, v161
	ds_write_b32 v176, v172 offset:38912
	v_cvt_pk_bf16_f32 v174, v172, v172
	ds_write_b16 v175, v174 offset:24320
	s_waitcnt lgkmcnt(14)
	v_lshlrev_b32_e32 v162, 16, v162
	v_lshlrev_b32_e32 v163, 16, v163
	v_lshlrev_b32_e32 v164, 16, v164
	v_lshlrev_b32_e32 v165, 16, v165
	v_fma_f32 v173, v75, v162, v78
	v_fmac_f32_e32 v173, v76, v163
	v_fmac_f32_e32 v173, v77, v164
	v_fmac_f32_e32 v173, v79, v165
	ds_write_b32 v176, v173 offset:40960
	v_cvt_pk_bf16_f32 v174, v173, v173
	ds_write_b16 v175, v174 offset:25472
	s_add_i32 s0, s9, s16
	s_cmpk_gt_i32 s0, 0x43
	s_cbranch_scc1 .LBB0_565
	s_cmp_lt_i32 s0, 4
	s_movk_i32 s0, 0x1100
	v_ashrrev_i32_e32 v0, 3, v80
	s_cselect_b32 s20, 0, 0x100
	s_cselect_b32 s27, 0x100, s0
	v_add_u32_e32 v0, s5, v0
	v_cmp_le_i32_e32 vcc, s20, v0
	v_cmp_gt_i32_e64 s[0:1], s27, v0
	v_mov_b32_e32 v220, v221
	s_and_b64 s[38:39], vcc, s[0:1]
	v_mov_b64_e32 v[64:65], v[220:221]
	v_mov_b64_e32 v[66:67], v[220:221]
	s_and_saveexec_b64 s[0:1], s[38:39]
	s_cbranch_execz .LBB0_562
	v_mov_b32_e32 v1, v221
	v_lshl_add_u64 v[0:1], s[36:37], 0, v[0:1]
	v_mov_b64_e32 v[2:3], s[40:41]
	v_mad_u64_u32 v[2:3], s[38:39], v0, s18, v[2:3]
	v_mov_b32_e32 v0, v3
	v_mad_u64_u32 v[0:1], s[38:39], v1, s18, v[0:1]
	v_mov_b32_e32 v3, v0
	v_lshlrev_b32_e32 v0, 4, v80
	v_and_b32_e32 v220, 0x70, v0
	v_lshl_add_u64 v[0:1], v[2:3], 0, v[220:221]
	global_load_dwordx4 v[64:67], v[0:1], off
